# v25 plus P0 stragglers removed: rope table and sg_w conversion each spread over eight idle workgroups instead of one workgroup each
# baseline (speedup 1.0000x reference)
; __device__ __forceinline__ unsigned cvtpk(float lo, float hi) { f32x2 v = {lo, hi}; bf16x2_t b = __builtin_convertvector(v, bf16x2_t); return __builtin_bit_cast(unsigned, b); }
; __device__ __forceinline__ void p0_prologue(const Args& a, LAS unsigned char* lds, int tid, int wid, int lane, int G) {
;     ...
;     } else if ((int)blockIdx.x == G - 1) {
;         f32x2* tab = (f32x2*)(ws + WS_ROPE);
;         for (int i = tid; i < 64 * 64; i += 512) { const int pos = i >> 6, f = i & 63; const float freq = exp2f(-(float)f * (13.287712379549449f / 64.0f)); const float ang = (float)pos * freq;
;             tab[i] = (f32x2){cosf(ang), sinf(ang)}; }
;     } else if ((int)blockIdx.x == G - 2) {
;         bf16_t* sw = (bf16_t*)(ws + WS_SGW);
;         for (int i = tid; i < 8 * 128 * 128 / 2; i += 512) ((unsigned*)sw)[i] = cvtpk(a.sg_w[2 * i], a.sg_w[2 * i + 1]);
.LBB0_17:
	v_and_b32_e32 v177, 63, v176
	s_cmpk_gt_i32 s2, 0xbf
	s_mov_b64 s[4:5], -1
	s_cbranch_scc0 .LBB0_37
	s_sub_i32 s98, s2, s30
	s_add_i32 s98, s98, 10
	s_cmp_lt_u32 s98, 8
	s_cbranch_scc1 .LBB0_24
	s_add_i32 s98, s98, 8
	s_cmp_lt_u32 s98, 8
	s_cbranch_scc0 .LBB0_23
	v_lshlrev_b32_e32 v2, 2, v176
	v_mov_b32_e32 v3, 0
	v_lshl_add_u64 v[0:1], s[28:29], 0, v[2:3]
	s_mov_b64 s[4:5], 0x90000
	v_lshlrev_b32_e32 v2, 3, v176
	v_add_u32_e32 v4, 0xfffffe00, v176
	v_lshl_add_u64 v[0:1], v[0:1], 0, s[4:5]
	v_lshl_add_u64 v[2:3], s[44:45], 0, v[2:3]
	s_lshl_b32 s100, s98, 16
	s_mov_b32 s101, 0
	v_lshl_add_u64 v[2:3], v[2:3], 0, s[100:101]
	s_lshl_b32 s100, s98, 15
	v_lshl_add_u64 v[0:1], v[0:1], 0, s[100:101]
	s_mov_b64 s[4:5], 0
	s_mov_b64 s[8:9], 0x800
	s_mov_b64 s[10:11], 0x1000
	s_mov_b32 s3, 0xfdff
	s_movk_i32 s3, 1

; __device__ __forceinline__ void p0_prologue(const Args& a, LAS unsigned char* lds, int tid, int wid, int lane, int G) {
;     ...
;         f32x2* tab = (f32x2*)(ws + WS_ROPE);
;         for (int i = tid; i < 64 * 64; i += 512) { const int pos = i >> 6, f = i & 63; const float freq = exp2f(-(float)f * (13.287712379549449f / 64.0f)); const float ang = (float)pos * freq;
;             tab[i] = (f32x2){cosf(ang), sinf(ang)}; }
.LBB0_24:
	s_andn2_b64 vcc, exec, s[4:5]
	s_cbranch_vccnz .LBB0_36
	v_cvt_f32_ubyte0_e32 v0, v177
	v_mul_f32_e32 v1, 0xbe549a78, v0
	s_mov_b32 s3, 0xc2fc0000
	v_cmp_gt_f32_e32 vcc, s3, v1
	v_mov_b32_e32 v2, 0x42800000
	v_not_b32_e32 v4, 63
	v_cndmask_b32_e32 v2, 0, v2, vcc
	v_fmac_f32_e32 v2, 0xbe549a78, v0
	v_exp_f32_e32 v0, v2
	v_cndmask_b32_e32 v1, 0, v4, vcc
	s_mov_b64 s[4:5], 0x80000
	v_add_u32_e32 v6, 0xc00, v176
	v_ldexp_f32 v5, v0, v1
	v_lshlrev_b32_e32 v0, 3, v176
	v_mov_b32_e32 v1, 0
	v_lshl_add_u64 v[2:3], s[28:29], 0, v[0:1]
	v_lshl_add_u64 v[2:3], v[2:3], 0, s[4:5]
	s_lshl_b32 s100, s98, 12
	s_mov_b32 s101, 0
	v_lshl_add_u64 v[2:3], v[2:3], 0, s[100:101]
	v_lshrrev_b32_e32 v7, 6, v176
	s_lshl_b32 s99, s98, 3
	v_add_u32_e32 v7, s99, v7
	s_mov_b64 s[14:15], 0
	s_brev_b32 s3, 18
	s_mov_b32 s6, 0xfe5163ab
	s_mov_b32 s7, 0x3c439041
	s_mov_b32 s20, 0xdb629599
	s_mov_b32 s21, 0xf534ddc0
	s_mov_b32 s22, 0xfc2757d1
	s_mov_b32 s23, 0x4e441529
	s_mov_b32 s33, 0xa2f9836e
	s_mov_b32 s34, 0x3fc90fda
	v_mov_b32_e32 v8, 0x3c0881c4
	v_mov_b32_e32 v9, 0xbab64f3b
	s_brev_b32 s35, 1
	s_mov_b32 s44, 0x7f800000
	s_mov_b64 s[16:17], 0x1000
	s_movk_i32 s45, 0xdff
	v_not_b32_e32 v10, 31
	v_mov_b32_e32 v11, 0x7fc00000
	s_branch .LBB0_27
